# boundary-tile mask via VOP3 compares into scalar pairs (no nops/adds); alpha stays in its temp on the fast path
# speedup vs baseline: 1.0053x; 1.0002x over previous
; #define SBAR() __builtin_amdgcn_sched_barrier(0)
; #define QK_RD(d0, sl) do { if ((d0) < 8) { const int a_ = kbase ^ (((d0) & 7) << 5); KRD(f0[sl], a_, 0); KRD(f1[sl], a_, 32 * 256); } \
;                            else { const int a_ = rbase ^ (((d0) & 3) << 5); KRD(f0[sl], a_, 0); KRD(f1[sl], a_, 32 * 128); } } while (0)
; #define LGKM(n) asm volatile("s_waitcnt lgkmcnt(" #n ")" ::: "memory")
; __device__ __forceinline__ void mphase(bool has_pv, f32x16* o, int vb, bf16x8 pa0, bf16x8 pa1, bf16x8 pa2, bf16x8 pa3, f32x16& p0, f32x16& p1, int kbase, int rbase, const bf16x8* qr) {
;     ...
;     QK_RD(0, 0); QK_RD(1, 1);
;     p0 = f32x16{}; p1 = f32x16{};
; #pragma unroll
;     for (int d0 = 0; d0 < 12; ++d0) {
;         if (d0 + 2 < 12) { QK_RD(d0 + 2, (d0 + 2) % 3); LGKM(4); }
;         else if (d0 + 1 < 12) LGKM(2);
;         else LGKM(0);
;         SBAR();
;         p0 = __builtin_amdgcn_mfma_f32_32x32x16_bf16(f0[d0 % 3], qr[d0], p0, 0, 0, 0);
;         p1 = __builtin_amdgcn_mfma_f32_32x32x16_bf16(f1[d0 % 3], qr[d0], p1, 0, 0, 0);
;         SBAR(); }
; __device__ __forceinline__ void attn_block(const Ptrs& P, int b, int h, int qb, LAS char* lds) {
;     ...
;         { const int kb_ = x * KVBLK; if (kb_ + KVBLK - 1 > qlo) { const int dq = qm - kb_; const float NEG = -__builtin_inff();
; #pragma unroll
;             for (int r = 0; r < 16; ++r) { const int c_ = (r & 3) + 8 * (r >> 2); if (dq - c_ < 0) p0[r] = NEG; if (dq - c_ - 32 < 0) p1[r] = NEG; } } }
.Lattn_qk:
	s_waitcnt lgkmcnt(4)
	v_mfma_f32_32x32x16_bf16 v[84:99], v[68:71], v[100:103], v[224:239]
	v_mfma_f32_32x32x16_bf16 v[68:83], v[72:75], v[100:103], v[224:239]
	v_xor_b32_e32 v199, 0x60, v3
	ds_read_b128 v[216:219], v199 offset:0
	ds_read_b128 v[220:223], v199 offset:0x2000
	s_waitcnt lgkmcnt(4)
	v_mfma_f32_32x32x16_bf16 v[84:99], v[200:203], v[104:107], v[84:99]
	v_mfma_f32_32x32x16_bf16 v[68:83], v[204:207], v[104:107], v[68:83]
	v_xor_b32_e32 v199, 0x80, v3
	ds_read_b128 v[200:203], v199 offset:0
	ds_read_b128 v[204:207], v199 offset:0x2000
	s_waitcnt lgkmcnt(4)
	v_mfma_f32_32x32x16_bf16 v[84:99], v[208:211], v[108:111], v[84:99]
	v_mfma_f32_32x32x16_bf16 v[68:83], v[212:215], v[108:111], v[68:83]
	v_xor_b32_e32 v199, 0xa0, v3
	ds_read_b128 v[208:211], v199 offset:0
	ds_read_b128 v[212:215], v199 offset:0x2000
	s_waitcnt lgkmcnt(4)
	v_mfma_f32_32x32x16_bf16 v[84:99], v[216:219], v[112:115], v[84:99]
	v_mfma_f32_32x32x16_bf16 v[68:83], v[220:223], v[112:115], v[68:83]
	v_xor_b32_e32 v199, 0xc0, v3
	ds_read_b128 v[216:219], v199 offset:0
	ds_read_b128 v[220:223], v199 offset:0x2000
	s_waitcnt lgkmcnt(4)
	v_mfma_f32_32x32x16_bf16 v[84:99], v[200:203], v[116:119], v[84:99]
	v_mfma_f32_32x32x16_bf16 v[68:83], v[204:207], v[116:119], v[68:83]
	v_xor_b32_e32 v199, 0xe0, v3
	ds_read_b128 v[200:203], v199 offset:0
	ds_read_b128 v[204:207], v199 offset:0x2000
	s_waitcnt lgkmcnt(4)
	v_mfma_f32_32x32x16_bf16 v[84:99], v[208:211], v[120:123], v[84:99]
	v_mfma_f32_32x32x16_bf16 v[68:83], v[212:215], v[120:123], v[68:83]
	ds_read_b128 v[208:211], v197 offset:0
	ds_read_b128 v[212:215], v197 offset:0x1000
	s_waitcnt lgkmcnt(4)
	v_mfma_f32_32x32x16_bf16 v[84:99], v[216:219], v[124:127], v[84:99]
	v_mfma_f32_32x32x16_bf16 v[68:83], v[220:223], v[124:127], v[68:83]
	v_xor_b32_e32 v199, 32, v197
	ds_read_b128 v[216:219], v199 offset:0
	ds_read_b128 v[220:223], v199 offset:0x1000
	s_waitcnt lgkmcnt(4)
	v_mfma_f32_32x32x16_bf16 v[84:99], v[200:203], v[128:131], v[84:99]
	v_mfma_f32_32x32x16_bf16 v[68:83], v[204:207], v[128:131], v[68:83]
	v_xor_b32_e32 v199, 64, v197
	ds_read_b128 v[200:203], v199 offset:0
	ds_read_b128 v[204:207], v199 offset:0x1000
	s_waitcnt lgkmcnt(4)
	v_mfma_f32_32x32x16_bf16 v[84:99], v[208:211], v[132:135], v[84:99]
	v_mfma_f32_32x32x16_bf16 v[68:83], v[212:215], v[132:135], v[68:83]
	v_xor_b32_e32 v199, 0x60, v197
	ds_read_b128 v[208:211], v199 offset:0
	ds_read_b128 v[212:215], v199 offset:0x1000
	s_waitcnt lgkmcnt(4)
	v_mfma_f32_32x32x16_bf16 v[84:99], v[216:219], v[136:139], v[84:99]
	v_mfma_f32_32x32x16_bf16 v[68:83], v[220:223], v[136:139], v[68:83]
	s_waitcnt lgkmcnt(2)
	v_mfma_f32_32x32x16_bf16 v[84:99], v[200:203], v[140:143], v[84:99]
	v_mfma_f32_32x32x16_bf16 v[68:83], v[204:207], v[140:143], v[68:83]
	s_waitcnt lgkmcnt(0)
	v_mfma_f32_32x32x16_bf16 v[84:99], v[208:211], v[144:147], v[84:99]
	v_mfma_f32_32x32x16_bf16 v[68:83], v[212:215], v[144:147], v[68:83]
	s_setprio 0
	s_cmp_le_u32 s82, s75
	s_barrier
	s_cbranch_scc1 .LBB0_619
	v_add_u32_e32 v199, s81, v195
	v_cmp_gt_i32_e64 s[22:23], -16, v199
	v_cmp_gt_i32_e64 s[98:99], 16, v199
	v_cmp_gt_i32_e64 s[100:101], -15, v199
	v_cmp_gt_i32_e64 vcc, 17, v199
	v_cndmask_b32_e64 v84, v84, v191, s[22:23]
	v_cndmask_b32_e64 v68, v68, v191, s[98:99]
	v_cndmask_b32_e64 v85, v85, v191, s[100:101]
	v_cndmask_b32_e64 v69, v69, v191, vcc
	v_cmp_gt_i32_e64 s[22:23], -14, v199
	v_cmp_gt_i32_e64 s[98:99], 18, v199
	v_cmp_gt_i32_e64 s[100:101], -13, v199
	v_cmp_gt_i32_e64 vcc, 19, v199
	v_cndmask_b32_e64 v86, v86, v191, s[22:23]
	v_cndmask_b32_e64 v70, v70, v191, s[98:99]
	v_cndmask_b32_e64 v87, v87, v191, s[100:101]
	v_cndmask_b32_e64 v71, v71, v191, vcc
	v_cmp_gt_i32_e64 s[22:23], -8, v199
	v_cmp_gt_i32_e64 s[98:99], 24, v199
	v_cmp_gt_i32_e64 s[100:101], -7, v199
	v_cmp_gt_i32_e64 vcc, 25, v199
	v_cndmask_b32_e64 v88, v88, v191, s[22:23]
	v_cndmask_b32_e64 v72, v72, v191, s[98:99]
	v_cndmask_b32_e64 v89, v89, v191, s[100:101]
	v_cndmask_b32_e64 v73, v73, v191, vcc
	v_cmp_gt_i32_e64 s[22:23], -6, v199
	v_cmp_gt_i32_e64 s[98:99], 26, v199
	v_cmp_gt_i32_e64 s[100:101], -5, v199
	v_cmp_gt_i32_e64 vcc, 27, v199
	v_cndmask_b32_e64 v90, v90, v191, s[22:23]
	v_cndmask_b32_e64 v74, v74, v191, s[98:99]
	v_cndmask_b32_e64 v91, v91, v191, s[100:101]
	v_cndmask_b32_e64 v75, v75, v191, vcc
	v_cmp_gt_i32_e64 s[22:23], 0, v199
	v_cmp_gt_i32_e64 s[98:99], 32, v199
	v_cmp_gt_i32_e64 s[100:101], 1, v199
	v_cmp_gt_i32_e64 vcc, 33, v199
	v_cndmask_b32_e64 v92, v92, v191, s[22:23]
	v_cndmask_b32_e64 v76, v76, v191, s[98:99]
	v_cndmask_b32_e64 v93, v93, v191, s[100:101]
	v_cndmask_b32_e64 v77, v77, v191, vcc
	v_cmp_gt_i32_e64 s[22:23], 2, v199
	v_cmp_gt_i32_e64 s[98:99], 34, v199
	v_cmp_gt_i32_e64 s[100:101], 3, v199
	v_cmp_gt_i32_e64 vcc, 35, v199
	v_cndmask_b32_e64 v94, v94, v191, s[22:23]
	v_cndmask_b32_e64 v78, v78, v191, s[98:99]
	v_cndmask_b32_e64 v95, v95, v191, s[100:101]
	v_cndmask_b32_e64 v79, v79, v191, vcc
	v_cmp_gt_i32_e64 s[22:23], 8, v199
	v_cmp_gt_i32_e64 s[98:99], 40, v199
	v_cmp_gt_i32_e64 s[100:101], 9, v199
	v_cmp_gt_i32_e64 vcc, 41, v199
	v_cndmask_b32_e64 v96, v96, v191, s[22:23]
	v_cndmask_b32_e64 v80, v80, v191, s[98:99]
	v_cndmask_b32_e64 v97, v97, v191, s[100:101]
	v_cndmask_b32_e64 v81, v81, v191, vcc
	v_cmp_gt_i32_e64 s[22:23], 10, v199
	v_cmp_gt_i32_e64 s[98:99], 42, v199
	v_cmp_gt_i32_e64 s[100:101], 11, v199
	v_cmp_gt_i32_e64 vcc, 43, v199
	v_cndmask_b32_e64 v98, v98, v191, s[22:23]
	v_cndmask_b32_e64 v82, v82, v191, s[98:99]
	v_cndmask_b32_e64 v99, v99, v191, s[100:101]
	v_cndmask_b32_e64 v83, v83, v191, vcc

; __device__ __forceinline__ int crow(int r, int hi) { return (r & 3) + 8 * (r >> 2) + 4 * hi; }
; __device__ __forceinline__ void attn_block(const Ptrs& P, int b, int h, int qb, LAS char* lds) {
;     ...
; #pragma unroll
;         for (int r = 0; r < 16; ++r) { p0[r] = __builtin_amdgcn_exp2f(p0[r] - m_reg); p1[r] = __builtin_amdgcn_exp2f(p1[r] - m_reg); }
;         float ps = 0.f;
; #pragma unroll
;         for (int r = 0; r < 16; ++r) ps += p0[r];
; #pragma unroll
;         for (int r = 0; r < 16; ++r) ps += p1[r];
;         { auto sw_ = __builtin_amdgcn_permlane32_swap(__float_as_uint(ps), __float_as_uint(ps), false, false); ps = __uint_as_float(sw_[0]) + __uint_as_float(sw_[1]); }
;         l_reg = l_reg * alpha + ps;
;         PK4(p0, 0, pa0); PK4(p0, 8, pa1); PK4(p1, 0, pa2); PK4(p1, 8, pa3);
;         if (__any(alpha < 1.f)) { if (hi == 0) al_l[r32] = alpha; asm volatile("s_waitcnt lgkmcnt(0)" ::: "memory");
; #pragma unroll
;             for (int d_ = 0; d_ < 4; ++d_)
; #pragma unroll
;                 for (int r = 0; r < 16; ++r) o[d_][r] *= al_l[crow(r, hi)]; }
.Lattn_exp:
	v_exp_f32_e32 v84, v84
	v_exp_f32_e32 v85, v85
	v_exp_f32_e32 v86, v86
	v_exp_f32_e32 v87, v87
	v_exp_f32_e32 v88, v88
	v_exp_f32_e32 v89, v89
	v_exp_f32_e32 v90, v90
	v_exp_f32_e32 v91, v91
	v_exp_f32_e32 v92, v92
	v_exp_f32_e32 v93, v93
	v_exp_f32_e32 v94, v94
	v_exp_f32_e32 v95, v95
	v_exp_f32_e32 v96, v96
	v_exp_f32_e32 v97, v97
	v_exp_f32_e32 v98, v98
	v_exp_f32_e32 v99, v99
	v_exp_f32_e32 v68, v68
	v_add_f32_e32 v199, v84, v85
	v_exp_f32_e32 v69, v69
	v_add_f32_e32 v201, v86, v87
	v_exp_f32_e32 v70, v70
	v_add_f32_e32 v202, v88, v89
	v_exp_f32_e32 v71, v71
	v_add_f32_e32 v203, v90, v91
	v_exp_f32_e32 v72, v72
	v_add_f32_e32 v199, v92, v199
	v_exp_f32_e32 v73, v73
	v_add_f32_e32 v201, v93, v201
	v_exp_f32_e32 v74, v74
	v_add_f32_e32 v202, v94, v202
	v_exp_f32_e32 v75, v75
	v_add_f32_e32 v203, v95, v203
	v_exp_f32_e32 v76, v76
	v_add_f32_e32 v199, v96, v199
	v_exp_f32_e32 v77, v77
	v_add_f32_e32 v201, v97, v201
	v_exp_f32_e32 v78, v78
	v_add_f32_e32 v202, v98, v202
	v_exp_f32_e32 v79, v79
	v_add_f32_e32 v203, v99, v203
	v_exp_f32_e32 v80, v80
	v_exp_f32_e32 v81, v81
	v_exp_f32_e32 v82, v82
	v_exp_f32_e32 v83, v83
	v_add_f32_e32 v199, v68, v199
	v_add_f32_e32 v201, v69, v201
	v_add_f32_e32 v202, v70, v202
	v_add_f32_e32 v203, v71, v203
	v_add_f32_e32 v199, v72, v199
	v_add_f32_e32 v201, v73, v201
	v_add_f32_e32 v202, v74, v202
	v_add_f32_e32 v203, v75, v203
	v_add_f32_e32 v199, v76, v199
	v_add_f32_e32 v201, v77, v201
	v_add_f32_e32 v202, v78, v202
	v_add_f32_e32 v203, v79, v203
	v_add_f32_e32 v199, v80, v199
	v_add_f32_e32 v201, v81, v201
	v_add_f32_e32 v202, v82, v202
	v_add_f32_e32 v203, v83, v203
	v_add_f32_e32 v199, v199, v201
	v_add_f32_e32 v202, v202, v203
	v_cvt_pk_bf16_f32 v83, v82, v83
	v_cvt_pk_bf16_f32 v82, v80, v81
	v_cvt_pk_bf16_f32 v81, v78, v79
	v_cvt_pk_bf16_f32 v80, v76, v77
	v_cvt_pk_bf16_f32 v76, v68, v69
	v_cvt_pk_bf16_f32 v77, v70, v71
	v_cvt_pk_bf16_f32 v78, v72, v73
	v_cvt_pk_bf16_f32 v79, v74, v75
	v_cvt_pk_bf16_f32 v68, v84, v85
	v_cvt_pk_bf16_f32 v69, v86, v87
	v_cvt_pk_bf16_f32 v70, v88, v89
	v_cvt_pk_bf16_f32 v71, v90, v91
	v_add_f32_e32 v85, v199, v202
	v_cvt_pk_bf16_f32 v72, v92, v93
	v_cvt_pk_bf16_f32 v73, v94, v95
	v_cvt_pk_bf16_f32 v74, v96, v97
	v_cvt_pk_bf16_f32 v75, v98, v99
	s_cmp_eq_u64 s[22:23], exec
	s_cbranch_scc1 .LBB0_623
	v_mov_b32_e32 v84, v200
	s_and_saveexec_b64 s[22:23], s[0:1]
	ds_write_b32 v194, v84 offset:128
	s_or_b64 exec, exec, s[22:23]
	s_waitcnt lgkmcnt(0)
	ds_read_b128 v[88:91], v193 offset:224
	ds_read_b128 v[92:95], v193 offset:192
	ds_read_b128 v[96:99], v193 offset:160
	ds_read_b128 v[200:203], v193 offset:128
	s_waitcnt lgkmcnt(3)
	v_pk_mul_f32 v[66:67], v[66:67], v[90:91]
	s_waitcnt lgkmcnt(2)
	v_pk_mul_f32 v[62:63], v[62:63], v[94:95]
	s_waitcnt lgkmcnt(1)
	v_pk_mul_f32 v[58:59], v[58:59], v[98:99]
	s_waitcnt lgkmcnt(0)
	v_pk_mul_f32 v[54:55], v[54:55], v[202:203]
	v_pk_mul_f32 v[64:65], v[64:65], v[88:89]
	v_pk_mul_f32 v[60:61], v[60:61], v[92:93]
	v_pk_mul_f32 v[56:57], v[56:57], v[96:97]
	v_pk_mul_f32 v[52:53], v[52:53], v[200:201]
	v_pk_mul_f32 v[50:51], v[50:51], v[90:91]
	v_pk_mul_f32 v[46:47], v[46:47], v[94:95]
	v_pk_mul_f32 v[42:43], v[42:43], v[98:99]
	v_pk_mul_f32 v[38:39], v[38:39], v[202:203]
	v_pk_mul_f32 v[48:49], v[48:49], v[88:89]
	v_pk_mul_f32 v[44:45], v[44:45], v[92:93]
	v_pk_mul_f32 v[40:41], v[40:41], v[96:97]
	v_pk_mul_f32 v[36:37], v[36:37], v[200:201]
	v_pk_mul_f32 v[34:35], v[34:35], v[90:91]
	v_pk_mul_f32 v[30:31], v[30:31], v[94:95]
	v_pk_mul_f32 v[26:27], v[26:27], v[98:99]
	v_pk_mul_f32 v[22:23], v[22:23], v[202:203]
	v_pk_mul_f32 v[32:33], v[32:33], v[88:89]
	v_pk_mul_f32 v[28:29], v[28:29], v[92:93]
	v_pk_mul_f32 v[24:25], v[24:25], v[96:97]
	v_pk_mul_f32 v[20:21], v[20:21], v[200:201]
	v_pk_mul_f32 v[18:19], v[18:19], v[90:91]
	v_pk_mul_f32 v[14:15], v[14:15], v[94:95]
	v_pk_mul_f32 v[10:11], v[10:11], v[98:99]
	v_pk_mul_f32 v[6:7], v[6:7], v[202:203]
	v_pk_mul_f32 v[16:17], v[16:17], v[88:89]
	v_pk_mul_f32 v[12:13], v[12:13], v[92:93]
	v_pk_mul_f32 v[8:9], v[8:9], v[96:97]
	v_pk_mul_f32 v[4:5], v[4:5], v[200:201]
	v_mov_b32_e32 v200, v84

; __device__ __forceinline__ int crow(int r, int hi) { return (r & 3) + 8 * (r >> 2) + 4 * hi; }
; #define SLOAD(t) do { const int so_ = (t) * (KVBLK * 256); \
;         st_k0 = BLD(srdK, gofk, so_); st_k1 = BLD(srdK, gofk, so_ + 8192); st_v0 = BLD(srdV, gofk, so_); st_v1 = BLD(srdV, gofk, so_ + 8192); st_r = BLD(srdR, gofr, (t) * (KVBLK * 128)); } while (0)
; #define SWRITE(ts, v3) do { const int kb_ = ((ts) & 1) * SHM_K, rb_ = ((ts) & 1) * SHM_R, vb_ = (v3) * SHM_V; \
;         *(LAS bf16x8*)(lds + kb_ + kws) = st_k0; *(LAS bf16x8*)(lds + kb_ + kws + 32 * 256) = st_k1; \
;         *(LAS bf16x8*)(lds + vb_ + vst0) = st_v0; *(LAS bf16x8*)(lds + vb_ + vst1) = st_v1; *(LAS bf16x8*)(lds + rb_ + rws) = st_r; } while (0)
; __device__ __forceinline__ void attn_block(const Ptrs& P, int b, int h, int qb, LAS char* lds) {
;     ...
;         l_reg = l_reg * alpha + ps;
;         PK4(p0, 0, pa0); PK4(p0, 8, pa1); PK4(p1, 0, pa2); PK4(p1, 8, pa3);
;         if (__any(alpha < 1.f)) { if (hi == 0) al_l[r32] = alpha; asm volatile("s_waitcnt lgkmcnt(0)" ::: "memory");
; #pragma unroll
;             for (int d_ = 0; d_ < 4; ++d_)
; #pragma unroll
;                 for (int r = 0; r < 16; ++r) o[d_][r] *= al_l[crow(r, hi)]; }
;         if (ts < NT) SWRITE(ts, ts3);
;         if (ts + 1 < NT) SLOAD(ts + 1);
;         ++ts; ts3 = ts3 == 2 ? 0 : ts3 + 1;
;         __syncthreads();
.LBB0_627:
	s_add_i32 s22, s83, 1
	s_cmp_lg_u32 s83, 2
	s_cselect_b32 s39, s22, 0
	s_and_b64 s[22:23], exec, s[56:57]
	s_cselect_b32 s83, s83, s39
	s_add_i32 s22, s38, 1
	s_cmp_lg_u32 s38, 2
	s_cselect_b32 s38, s22, 0
	s_sub_i32 s81, s81, 64
	s_addk_i32 s78, 0x2000
	s_addk_i32 s79, 0x4000
	s_add_i32 s22, s80, s81
	s_add_i32 s82, s82, 64
	s_add_i32 s77, s77, 1
	v_fma_f32 v198, v198, v200, v85
	v_xor_b32_e32 v3, 0x4000, v3
	v_xor_b32_e32 v197, 0x2000, v197
	s_cmp_eq_u32 s22, 0
	s_waitcnt lgkmcnt(0)
	s_barrier
	s_cbranch_scc1 .LBB0_629
	s_branch .LBB0_615

; __global__ void __launch_bounds__(NWAVES * 64, 2) hybrid_fwd(Args args) {
	.amdhsa_kernel _Z10hybrid_fwd4Args
		.amdhsa_group_segment_fixed_size 0
		.amdhsa_private_segment_fixed_size 0
		.amdhsa_kernarg_size 480
		.amdhsa_user_sgpr_count 2
		.amdhsa_user_sgpr_dispatch_ptr 0
		.amdhsa_user_sgpr_queue_ptr 0
		.amdhsa_user_sgpr_kernarg_segment_ptr 1
		.amdhsa_user_sgpr_dispatch_id 0
		.amdhsa_user_sgpr_kernarg_preload_length 0
		.amdhsa_user_sgpr_kernarg_preload_offset 0
		.amdhsa_user_sgpr_private_segment_size 0
		.amdhsa_uses_dynamic_stack 0
		.amdhsa_enable_private_segment 0
		.amdhsa_system_sgpr_workgroup_id_x 1
		.amdhsa_system_sgpr_workgroup_id_y 0
		.amdhsa_system_sgpr_workgroup_id_z 0
		.amdhsa_system_sgpr_workgroup_info 0
		.amdhsa_system_vgpr_workitem_id 0
		.amdhsa_next_free_vgpr 256
		.amdhsa_next_free_sgpr 102
		.amdhsa_accum_offset 256
		.amdhsa_reserve_vcc 1
		.amdhsa_float_round_mode_32 0
		.amdhsa_float_round_mode_16_64 0
		.amdhsa_float_denorm_mode_32 3
		.amdhsa_float_denorm_mode_16_64 3
		.amdhsa_dx10_clamp 1
		.amdhsa_ieee_mode 1
		.amdhsa_fp16_overflow 0
		.amdhsa_tg_split 0
		.amdhsa_exception_fp_ieee_invalid_op 0
		.amdhsa_exception_fp_denorm_src 0
		.amdhsa_exception_fp_ieee_div_zero 0
		.amdhsa_exception_fp_ieee_overflow 0
		.amdhsa_exception_fp_ieee_underflow 0
		.amdhsa_exception_fp_ieee_inexact 0
		.amdhsa_exception_int_div_zero 0
	.end_amdhsa_kernel

; __global__ void __launch_bounds__(NWAVES * 64, 2) hybrid_fwd(Args args) {
amdhsa.kernels:
  - .agpr_count:     0
    .args:
      - .offset:         0
        .size:           224
        .value_kind:     by_value
      - .offset:         224
        .size:           4
        .value_kind:     hidden_block_count_x
      - .offset:         228
        .size:           4
        .value_kind:     hidden_block_count_y
      - .offset:         232
        .size:           4
        .value_kind:     hidden_block_count_z
      - .offset:         236
        .size:           2
        .value_kind:     hidden_group_size_x
      - .offset:         238
        .size:           2
        .value_kind:     hidden_group_size_y
      - .offset:         240
        .size:           2
        .value_kind:     hidden_group_size_z
      - .offset:         242
        .size:           2
        .value_kind:     hidden_remainder_x
      - .offset:         244
        .size:           2
        .value_kind:     hidden_remainder_y
      - .offset:         246
        .size:           2
        .value_kind:     hidden_remainder_z
      - .offset:         264
        .size:           8
        .value_kind:     hidden_global_offset_x
      - .offset:         272
        .size:           8
        .value_kind:     hidden_global_offset_y
      - .offset:         280
        .size:           8
        .value_kind:     hidden_global_offset_z
      - .offset:         288
        .size:           2
        .value_kind:     hidden_grid_dims
      - .offset:         344
        .size:           4
        .value_kind:     hidden_dynamic_lds_size
    .group_segment_fixed_size: 0
    .kernarg_segment_align: 8
    .kernarg_segment_size: 480
    .language:       OpenCL C
    .language_version:
      - 2
      - 0
    .max_flat_workgroup_size: 512
    .name:           _Z10hybrid_fwd4Args
    .private_segment_fixed_size: 0
    .sgpr_count:     108
    .sgpr_spill_count: 54
    .symbol:         _Z10hybrid_fwd4Args.kd
    .uniform_work_group_size: 1
    .uses_dynamic_stack: false
    .vgpr_count:     256
    .vgpr_spill_count: 0
    .wavefront_size: 64
